# bundle: S5 sample step requests all four samples' rows up front; residual-updating sample GEMMs request their rows at unit start; gate|up unit decode by shift/mask
# baseline (speedup 1.0000x reference)
.LBB11_789:
	s_or_b64 exec, exec, s[10:11]
	v_readlane_b32 s58, v248, 14
	v_readlane_b32 s59, v248, 15
	v_mov_b32_e32 v0, v199
	v_mov_b32_e32 v42, v198
	s_barrier
	s_load_dwordx4 s[44:47], s[58:59], 0x130
	s_load_dwordx4 s[8:11], s[58:59], 0xb8
	v_readlane_b32 s0, v242, 3
	s_or_b32 s12, s26, s0
	s_lshl_b32 s0, s12, 6
	s_mov_b32 s1, s61
	v_ashrrev_i32_e32 v43, 31, v42
	v_lshl_add_u64 v[2:3], v[42:43], 0, s[0:1]
	s_waitcnt lgkmcnt(0)
	v_lshl_add_u64 v[4:5], v[2:3], 3, s[46:47]
	s_mov_b32 s0, 0x35400000
	v_lshlrev_b64 v[2:3], 7, v[2:3]
	v_readlane_b32 s14, v242, 12
	v_add_co_u32_e32 v6, vcc, s0, v4
	v_lshl_add_u64 v[2:3], s[46:47], 0, v[2:3]
	s_mov_b64 s[0:1], 0x35500000
	v_readlane_b32 s15, v242, 13
	v_lshl_add_u64 v[30:31], v[2:3], 0, s[0:1]
	s_or_b64 s[0:1], s[60:61], s[14:15]
	s_lshl_b64 s[0:1], s[0:1], 6
	v_addc_co_u32_e32 v7, vcc, 0, v5, vcc
	v_lshl_add_u64 v[4:5], s[0:1], 0, v[42:43]
	s_mov_b32 s0, 0x35500000
	v_add_co_u32_e32 v2, vcc, s0, v2
	v_lshlrev_b64 v[4:5], 2, v[4:5]
	s_nop 0
	v_addc_co_u32_e32 v3, vcc, 0, v3, vcc
	v_lshl_add_u64 v[36:37], s[8:9], 0, v[4:5]
	v_lshl_add_u64 v[38:39], s[10:11], 0, v[4:5]
	global_load_dwordx4 v[2:5], v[2:3], off
	s_nop 0
	global_load_dwordx2 v[34:35], v[6:7], off
	s_nop 0
	global_load_dwordx4 v[6:9], v[30:31], off offset:16
	global_load_dwordx4 v[10:13], v[30:31], off offset:32
	global_load_dwordx4 v[14:17], v[30:31], off offset:48
	global_load_dword v0, v[36:37], off
	global_load_dword v60, v[36:37], off offset:256
	global_load_dword v61, v[36:37], off offset:512
	global_load_dword v62, v[36:37], off offset:768
	global_load_dword v63, v[36:37], off offset:1024
	global_load_dword v64, v[36:37], off offset:1280
	global_load_dword v65, v[36:37], off offset:1536
	global_load_dword v66, v[36:37], off offset:1792
	global_load_dword v67, v[38:39], off
	global_load_dword v68, v[38:39], off offset:256
	global_load_dword v69, v[38:39], off offset:512
	global_load_dword v70, v[38:39], off offset:768
	global_load_dword v71, v[38:39], off offset:1024
	global_load_dword v72, v[38:39], off offset:1280
	global_load_dword v73, v[38:39], off offset:1536
	global_load_dword v74, v[38:39], off offset:1792
	global_load_dwordx4 v[18:21], v[30:31], off offset:64
	global_load_dwordx4 v[22:25], v[30:31], off offset:80
	global_load_dwordx4 v[26:29], v[30:31], off offset:96
	s_nop 0
	global_load_dwordx4 v[30:33], v[30:31], off offset:112
	s_nop 0
	global_load_dword v75, v[36:37], off offset:2048
	global_load_dword v76, v[36:37], off offset:2304
	global_load_dword v77, v[36:37], off offset:2560
	global_load_dword v78, v[36:37], off offset:2816
	global_load_dword v79, v[36:37], off offset:3072
	global_load_dword v80, v[36:37], off offset:3328
	global_load_dword v81, v[36:37], off offset:3584
	global_load_dword v82, v[36:37], off offset:3840
	global_load_dword v83, v[38:39], off offset:2048
	global_load_dword v84, v[38:39], off offset:2304
	global_load_dword v85, v[38:39], off offset:2560
	global_load_dword v86, v[38:39], off offset:2816
	global_load_dword v87, v[38:39], off offset:3072
	global_load_dword v88, v[38:39], off offset:3328
	global_load_dword v89, v[38:39], off offset:3584
	global_load_dword v90, v[38:39], off offset:3840
	v_readlane_b32 s6, v242, 6
	s_lshl_b32 s0, s34, 7
	v_readlane_b32 s7, v242, 7
	s_add_i32 s0, s6, s0
	s_lshr_b64 s[6:7], s[50:51], 1
	s_lshr_b32 s7, s51, 1
	s_load_dwordx4 s[48:51], s[58:59], 0x20
	s_load_dwordx2 s[8:9], s[58:59], 0x58
	s_mul_i32 s7, s7, 0x41000
	s_mul_hi_u32 s10, s6, 0x41000
	s_add_i32 s68, s10, s7
	s_mul_i32 s69, s6, 0x41000
	v_readlane_b32 s6, v242, 54
	s_ashr_i32 s1, s0, 31
	v_readlane_b32 s7, v242, 55
	s_lshl_b32 s60, s6, 10
	s_lshl_b64 s[0:1], s[0:1], 12
	s_lshl_b64 s[6:7], s[60:61], 2
	s_waitcnt lgkmcnt(0)
	s_add_u32 s6, s8, s6
	s_addc_u32 s7, s9, s7
	s_lshl_b32 s8, s14, 2
	s_add_u32 s56, s6, s8
	s_addc_u32 s57, s7, 0
	v_readlane_b32 s6, v242, 14
	v_readlane_b32 s7, v242, 15
	s_or_b64 s[0:1], s[6:7], s[0:1]
	s_lshl_b32 s60, s12, 4
	v_lshl_add_u64 v[36:37], s[0:1], 0, v[42:43]
	v_readlane_b32 s0, v242, 4
	v_readlane_b32 s1, v242, 5
	s_add_u32 s88, s46, s0
	s_addc_u32 s89, s47, s1
	v_readlane_b32 s0, v242, 8
	s_add_u32 s0, s46, s0
	v_readlane_b32 s1, v242, 9
	s_addc_u32 s1, s47, s1
	v_lshlrev_b64 v[40:41], 2, v[36:37]
	s_add_u32 s46, s0, s69
	s_mov_b32 s70, s34
	v_cmp_gt_i32_e32 vcc, 16, v42
	v_cmp_eq_u32_e64 s[10:11], 0, v42
	v_cmp_eq_u32_e64 s[12:13], 1, v42
	v_cmp_eq_u32_e64 s[14:15], 2, v42
	v_cmp_eq_u32_e64 s[16:17], 3, v42
	v_cmp_eq_u32_e64 s[18:19], 4, v42
	v_cmp_eq_u32_e64 s[20:21], 5, v42
	v_cmp_eq_u32_e64 s[22:23], 6, v42
	v_cmp_eq_u32_e64 s[24:25], 7, v42
	v_cmp_eq_u32_e64 s[26:27], 8, v42
	v_cmp_eq_u32_e64 s[28:29], 9, v42
	v_cmp_eq_u32_e64 s[30:31], 10, v42
	v_cmp_eq_u32_e64 s[34:35], 11, v42
	v_cmp_eq_u32_e64 s[36:37], 12, v42
	v_cmp_eq_u32_e64 s[38:39], 13, v42
	v_cmp_eq_u32_e64 s[40:41], 14, v42
	v_cmp_eq_u32_e64 s[42:43], 15, v42
	v_lshl_add_u64 v[36:37], s[44:45], 0, v[40:41]
	v_lshl_add_u64 v[38:39], s[50:51], 0, v[40:41]
	v_lshl_add_u64 v[40:41], s[48:49], 0, v[40:41]
	v_lshl_add_u64 v[42:43], v[42:43], 1, v[184:185]
	s_addc_u32 s47, s1, s68
	global_load_dword v234, v1, s[46:47]
	s_add_u32 s100, s88, 0x0
	s_addc_u32 s101, s89, 0
	global_load_dword v234, v209, s[100:101]
	global_load_dword v234, v210, s[100:101]
	s_add_u32 s100, s88, 0x15900000
	s_addc_u32 s101, s89, 0
	global_load_dword v234, v1, s[100:101] offset:16
	s_add_u32 s100, s88, 0x11800000
	s_addc_u32 s101, s89, 0
	global_load_dword v234, v1, s[100:101] offset:16
	s_mov_b64 s[100:101], 0x0
	v_lshl_add_u64 v[232:233], v[40:41], 0, s[100:101]
	global_load_dword v234, v[232:233], off
	v_lshl_add_u64 v[232:233], v[38:39], 0, s[100:101]
	global_load_dword v234, v[232:233], off
	global_load_dword v234, v1, s[46:47] offset:128
	s_add_u32 s100, s88, 0x10000
	s_addc_u32 s101, s89, 0
	global_load_dword v234, v209, s[100:101]
	global_load_dword v234, v210, s[100:101]
	s_add_u32 s100, s88, 0x15910000
	s_addc_u32 s101, s89, 0
	global_load_dword v234, v1, s[100:101] offset:16
	s_add_u32 s100, s88, 0x11810000
	s_addc_u32 s101, s89, 0
	global_load_dword v234, v1, s[100:101] offset:16
	s_mov_b64 s[100:101], 0x80000
	v_lshl_add_u64 v[232:233], v[40:41], 0, s[100:101]
	global_load_dword v234, v[232:233], off
	v_lshl_add_u64 v[232:233], v[38:39], 0, s[100:101]
	global_load_dword v234, v[232:233], off
	global_load_dword v234, v1, s[46:47] offset:256
	s_add_u32 s100, s88, 0x20000
	s_addc_u32 s101, s89, 0
	global_load_dword v234, v209, s[100:101]
	global_load_dword v234, v210, s[100:101]
	s_add_u32 s100, s88, 0x15920000
	s_addc_u32 s101, s89, 0
	global_load_dword v234, v1, s[100:101] offset:16
	s_add_u32 s100, s88, 0x11820000
	s_addc_u32 s101, s89, 0
	global_load_dword v234, v1, s[100:101] offset:16
	s_mov_b64 s[100:101], 0x100000
	v_lshl_add_u64 v[232:233], v[40:41], 0, s[100:101]
	global_load_dword v234, v[232:233], off
	v_lshl_add_u64 v[232:233], v[38:39], 0, s[100:101]
	global_load_dword v234, v[232:233], off
	global_load_dword v234, v1, s[46:47] offset:384
	s_add_u32 s100, s88, 0x30000
	s_addc_u32 s101, s89, 0
	global_load_dword v234, v209, s[100:101]
	global_load_dword v234, v210, s[100:101]
	s_add_u32 s100, s88, 0x15930000
	s_addc_u32 s101, s89, 0
	global_load_dword v234, v1, s[100:101] offset:16
	s_add_u32 s100, s88, 0x11830000
	s_addc_u32 s101, s89, 0
	global_load_dword v234, v1, s[100:101] offset:16
	s_mov_b64 s[100:101], 0x180000
	v_lshl_add_u64 v[232:233], v[40:41], 0, s[100:101]
	global_load_dword v234, v[232:233], off
	v_lshl_add_u64 v[232:233], v[38:39], 0, s[100:101]
	global_load_dword v234, v[232:233], off
	s_mov_b64 s[90:91], 0
	s_branch .LBB11_791

.LBB11_2564:
	s_add_i32 s60, s60, 1
	s_lshl_b64 s[0:1], s[60:61], 4
	s_add_u32 s22, s0, s33
	s_addc_u32 s23, s1, s93
	v_cmp_gt_i64_e32 vcc, s[22:23], v[188:189]
	v_cmp_lt_i64_e64 s[12:13], s[22:23], v[186:187]
	s_mov_b32 s8, -1
	s_cbranch_vccnz .LBB11_2566
	s_ashr_i32 s0, s22, 31
	s_lshr_b32 s0, s0, 29
	s_add_i32 s0, s22, s0
	s_ashr_i32 s1, s0, 3
	s_and_b32 s0, s0, -8
	s_sub_i32 s0, s22, s0
	s_cmp_lt_i32 s0, 0
	s_cselect_b32 s8, 12, 11
	s_mul_i32 s0, s0, s8
	s_add_i32 s0, s0, s1
	s_lshr_b32 s43, s0, 2
	s_and_b32 s0, s0, 3
	s_add_i32 s8, s0, s92
	s_lshl_b32 s45, s8, 19
	s_lshl_b32 s44, s43, 19
	s_mov_b32 s46, s8
